# FFN1 down-weight conversion moved from P0 into the FFN1 GEMM tail; w_in/w_out conversion into the idle workgroups of the FFN1-down GEMM second round
# speedup vs baseline: 1.0283x; 1.0074x over previous
; __device__ __forceinline__ int fresh_tid(int wv) { int l; asm volatile("v_mbcnt_lo_u32_b32 %0, -1, 0\n\tv_mbcnt_hi_u32_b32 %0, -1, %0" : "=v"(l)); return wv * 64 + l; }
; #define LAS __attribute__((address_space(3)))
; __device__ __forceinline__ TDesc tconv_desc(const float* wg, const float* wu, const float* wd, const float* win, const float* wout, unsigned char* ws, int i) {
;     TDesc d; int mode = 0, tile = i;
;     if (i < 704) { d.W = wg; d.Bt = (bf16_t*)(ws + WS_WGU); d.K = 1024; d.N = DFF; mode = 1; }
;     else if (i < 1408) { d.W = wu; d.Bt = (bf16_t*)(ws + WS_WGU); d.K = 1024; d.N = DFF; mode = 2; tile = i - 704; }
;     else if (i < 2112) { d.W = wd; d.Bt = (bf16_t*)(ws + WS_WD); d.K = DFF; d.N = 1024; tile = i - 1408; }
;     else if (i < 3072) { d.W = win; d.Bt = (bf16_t*)(ws + WS_WIN); d.K = 1024; d.N = NCOLS; tile = i - 2112; }
;     else { d.W = wout; d.Bt = (bf16_t*)(ws + WS_WOUT); d.K = 1024; d.N = 1024; tile = i - 3072; }
;     const int nkt = d.K / 64; const int kt = tile % nkt, nt = tile / nkt; d.k0 = kt * 64; d.n0 = nt * 64;
;     d.brow0 = mode == 0 ? d.n0 : ((d.n0 >> 7) * 256 + (d.n0 & 127) + (mode == 2 ? 128 : 0));
;     return d;
; }
; __device__ __forceinline__ void tconv_list(const float* wg, const float* wu, const float* wd, const float* win, const float* wout, unsigned char* ws, const int ntiles, LAS float* t, const int wv) {
;     const int tid = fresh_tid(wv); const int G = gridDim.x;
;     float cur[8], nxt[8];
;     int i = blockIdx.x;
;     if (i < ntiles) { const TDesc d = tconv_desc(wg, wu, wd, win, wout, ws, i);
; #pragma unroll
;         for (int e = 0; e < 8; ++e) { const int idx = e * 512 + tid, r = idx >> 6, c = idx & 63; cur[e] = __builtin_nontemporal_load(d.W + (size_t)(d.k0 + r) * d.N + d.n0 + c); } }
;     for (; i < ntiles; i += G) {
;         const TDesc d = tconv_desc(wg, wu, wd, win, wout, ws, i);
;         { const TDesc dn = tconv_desc(wg, wu, wd, win, wout, ws, i + G < ntiles ? i + G : i);
.LBB0_72:
	s_add_i32 s4, s7, s50
	s_cmpk_gt_i32 s4, 0x57f
	s_cselect_b64 s[30:31], -1, 0
	s_cmpk_lt_i32 s4, 0x580
	s_cselect_b32 s7, s4, s7
	s_cmpk_lt_i32 s7, 0x2c0
	s_cbranch_scc1 .LBB0_77
	s_cmpk_gt_u32 s7, 0x57f
	s_cbranch_scc0 .LBB0_78
	s_cmpk_gt_u32 s7, 0x83f
	s_cbranch_scc0 .LBB0_79
	s_cmpk_gt_u32 s7, 0xbff
	s_cbranch_scc0 .LBB0_80
	s_add_i32 s44, s7, 0xfffff400
	s_mov_b64 s[38:39], s[18:19]
	s_mov_b64 s[36:37], 0x400
	s_cbranch_execz .LBB0_81
	s_branch .LBB0_82

; __device__ __forceinline__ int fresh_tid(int wv) { int l; asm volatile("v_mbcnt_lo_u32_b32 %0, -1, 0\n\tv_mbcnt_hi_u32_b32 %0, -1, %0" : "=v"(l)); return wv * 64 + l; }
; #define LAS __attribute__((address_space(3)))
; __device__ __forceinline__ TDesc tconv_desc(const float* wg, const float* wu, const float* wd, const float* win, const float* wout, unsigned char* ws, int i) {
;     TDesc d; int mode = 0, tile = i;
;     if (i < 704) { d.W = wg; d.Bt = (bf16_t*)(ws + WS_WGU); d.K = 1024; d.N = DFF; mode = 1; }
;     else if (i < 1408) { d.W = wu; d.Bt = (bf16_t*)(ws + WS_WGU); d.K = 1024; d.N = DFF; mode = 2; tile = i - 704; }
;     else if (i < 2112) { d.W = wd; d.Bt = (bf16_t*)(ws + WS_WD); d.K = DFF; d.N = 1024; tile = i - 1408; }
;     else if (i < 3072) { d.W = win; d.Bt = (bf16_t*)(ws + WS_WIN); d.K = 1024; d.N = NCOLS; tile = i - 2112; }
;     else { d.W = wout; d.Bt = (bf16_t*)(ws + WS_WOUT); d.K = 1024; d.N = 1024; tile = i - 3072; }
;     const int nkt = d.K / 64; const int kt = tile % nkt, nt = tile / nkt; d.k0 = kt * 64; d.n0 = nt * 64;
;     d.brow0 = mode == 0 ? d.n0 : ((d.n0 >> 7) * 256 + (d.n0 & 127) + (mode == 2 ? 128 : 0));
;     return d;
; }
; __device__ __forceinline__ void tconv_list(const float* wg, const float* wu, const float* wd, const float* win, const float* wout, unsigned char* ws, const int ntiles, LAS float* t, const int wv) {
;     const int tid = fresh_tid(wv); const int G = gridDim.x;
;     float cur[8], nxt[8];
;     int i = blockIdx.x;
;     if (i < ntiles) { const TDesc d = tconv_desc(wg, wu, wd, win, wout, ws, i);
; #pragma unroll
;         for (int e = 0; e < 8; ++e) { const int idx = e * 512 + tid, r = idx >> 6, c = idx & 63; cur[e] = __builtin_nontemporal_load(d.W + (size_t)(d.k0 + r) * d.N + d.n0 + c); } }
;     for (; i < ntiles; i += G) {
;         const TDesc d = tconv_desc(wg, wu, wd, win, wout, ws, i);
;         { const TDesc dn = tconv_desc(wg, wu, wd, win, wout, ws, i + G < ntiles ? i + G : i);
; #pragma unroll
;             for (int e = 0; e < 8; ++e) { const int idx = e * 512 + tid, r = idx >> 6, c = idx & 63; nxt[e] = __builtin_nontemporal_load(dn.W + (size_t)(dn.k0 + r) * dn.N + dn.n0 + c); } }
.LBB0_163:
	s_cmp_lt_u32 s2, 172
	s_cbranch_scc1 .Ltc1_skip
	v_writelane_b32 v40, s4, 4
	v_writelane_b32 v40, s5, 5
	v_writelane_b32 v40, s6, 6
	v_writelane_b32 v40, s7, 7
	v_writelane_b32 v40, s8, 8
	v_writelane_b32 v40, s9, 9
	v_writelane_b32 v40, s10, 10
	v_writelane_b32 v40, s11, 11
	v_writelane_b32 v40, s12, 12
	v_writelane_b32 v40, s13, 13
	v_writelane_b32 v40, s14, 14
	v_writelane_b32 v40, s15, 15
	v_writelane_b32 v40, s16, 16
	v_writelane_b32 v40, s17, 17
	v_writelane_b32 v40, s18, 18
	v_writelane_b32 v40, s19, 19
	v_writelane_b32 v40, s20, 20
	v_writelane_b32 v40, s21, 21
	v_writelane_b32 v40, s22, 22
	v_writelane_b32 v40, s23, 23
	v_writelane_b32 v40, s24, 24
	v_writelane_b32 v40, s25, 25
	v_writelane_b32 v40, s26, 26
	v_writelane_b32 v40, s27, 27
	v_writelane_b32 v40, s28, 28
	v_writelane_b32 v40, s29, 29
	v_writelane_b32 v40, s30, 30
	v_writelane_b32 v40, s31, 31
	s_load_dwordx2 s[24:25], s[0:1], 0xd8
	s_load_dwordx2 s[26:27], s[0:1], 0xd0
	s_load_dwordx2 s[18:19], s[0:1], 0x40
	v_mbcnt_lo_u32_b32 v0, -1, 0
	v_mbcnt_hi_u32_b32 v0, -1, v0
	s_lshr_b32 s28, s33, 6
	v_lshlrev_b32_e32 v1, 2, v0
	v_lshrrev_b32_e32 v2, 5, v0
	v_and_b32_e32 v3, 31, v0
	s_mul_i32 s7, s28, 260
	v_add_u32_e32 v5, s7, v1
	v_mul_u32_u24_e32 v6, 0x208, v3
	s_lshl_b32 s7, s28, 3
	v_lshl_add_u32 v6, v2, 2, v6
	v_add_u32_e32 v6, s7, v6
	v_lshlrev_b32_e32 v3, 2, v3
	s_sub_u32 s4, s2, 172
	s_waitcnt lgkmcnt(0)
	s_mov_b32 s7, s4
	s_mul_i32 s9, s7, 1490
	s_lshr_b32 s9, s9, 16
	s_mul_i32 s8, s9, 44
	s_sub_u32 s8, s7, s8
	s_mul_i32 s7, s8, 262144
	s_lshl_b32 s29, s9, 8
	s_add_u32 s7, s7, s29
	s_mul_i32 s29, s28, 4096
	s_add_u32 s7, s7, s29
	s_add_u32 s10, s18, s7
	s_addc_u32 s11, s19, 0
	s_lshl_b32 s7, s9, 6
	s_mul_i32 s7, s7, 5632
	s_lshl_b32 s29, s8, 7
	s_add_u32 s7, s7, s29
	s_mul_i32 s29, s28, 11264
	s_add_u32 s7, s7, s29
	s_add_u32 s12, s24, 0x1644800
	s_addc_u32 s13, s25, 0
	s_add_u32 s12, s12, s7
	s_addc_u32 s13, s13, 0
	s_mov_b32 s14, 32768
	s_mov_b32 s15, 90112
	s_movk_i32 s16, 5632

; __device__ __forceinline__ void tconv_list(const float* wg, const float* wu, const float* wd, const float* win, const float* wout, unsigned char* ws, const int ntiles, LAS float* t, const int wv) {
;     ...
;     for (; i < ntiles; i += G) {
;         const TDesc d = tconv_desc(wg, wu, wd, win, wout, ws, i);
;         { const TDesc dn = tconv_desc(wg, wu, wd, win, wout, ws, i + G < ntiles ? i + G : i);
; #pragma unroll
;             for (int e = 0; e < 8; ++e) { const int idx = e * 512 + tid, r = idx >> 6, c = idx & 63; nxt[e] = __builtin_nontemporal_load(dn.W + (size_t)(dn.k0 + r) * dn.N + dn.n0 + c); } }
.Ltc1_loop:
	s_add_u32 s4, s4, 84
	s_cmp_lt_u32 s4, 704
	s_cselect_b32 s31, 1, 0
	s_cbranch_scc0 .Ltc1_nonexta
	v_writelane_b32 v40, s8, 32
	v_writelane_b32 v40, s9, 33
	s_mov_b32 s7, s4
	s_mul_i32 s9, s7, 1490
	s_lshr_b32 s9, s9, 16
	s_mul_i32 s8, s9, 44
	s_sub_u32 s8, s7, s8
	s_mul_i32 s7, s8, 262144
	s_lshl_b32 s29, s9, 8
	s_add_u32 s7, s7, s29
	s_mul_i32 s29, s28, 4096
	s_add_u32 s7, s7, s29
	s_add_u32 s10, s18, s7
	s_addc_u32 s11, s19, 0
	s_lshl_b32 s7, s9, 6
	s_mul_i32 s7, s7, 5632
	s_lshl_b32 s29, s8, 7
	s_add_u32 s7, s7, s29
	s_mul_i32 s29, s28, 11264
	s_add_u32 s7, s7, s29
	s_add_u32 s12, s24, 0x1644800
	s_addc_u32 s13, s25, 0
	s_add_u32 s12, s12, s7
	s_addc_u32 s13, s13, 0
	s_mov_b32 s14, 32768
	s_mov_b32 s15, 90112
	s_movk_i32 s16, 5632

; __device__ __forceinline__ unsigned cvt_pk_bf16(float lo, float hi) { const f32x2_t v = {lo, hi}; const bf16x2_t b = __builtin_convertvector(v, bf16x2_t); return __builtin_bit_cast(unsigned, b); }
; __device__ __forceinline__ void tconv_list(const float* wg, const float* wu, const float* wd, const float* win, const float* wout, unsigned char* ws, const int ntiles, LAS float* t, const int wv) {
;     ...
; #pragma unroll
;         for (int e = 0; e < 8; ++e) { const int idx = e * 512 + tid, r = idx >> 6, c = idx & 63; t[r * 65 + c] = cur[e]; }
;         __syncthreads();
; #pragma unroll
;         for (int e = 0; e < 4; ++e) { const int idx = e * 512 + tid, n = idx >> 5, kp = idx & 31;
;             const unsigned w = pg8::cvt_pk_bf16(t[(2 * kp) * 65 + n], t[(2 * kp + 1) * 65 + n]);
;             *(unsigned*)(d.Bt + (size_t)(d.brow0 + n) * d.K + d.k0 + 2 * kp) = w; }
;         __syncthreads();
; #pragma unroll
;         for (int e = 0; e < 8; ++e) cur[e] = nxt[e];
.Ltc1_havea:
	ds_write_b32 v5, v8 offset:0
	ds_write_b32 v5, v9 offset:2080
	ds_write_b32 v5, v10 offset:4160
	ds_write_b32 v5, v11 offset:6240
	ds_write_b32 v5, v12 offset:8320
	ds_write_b32 v5, v13 offset:10400
	ds_write_b32 v5, v14 offset:12480
	ds_write_b32 v5, v15 offset:14560
	v_mad_u32_u24 v4, v2, s30, v3
	s_waitcnt lgkmcnt(0)
	s_barrier
	ds_read2_b32 v[24:25], v6 offset0:0 offset1:65
	ds_read2_b32 v[26:27], v6 offset0:16 offset1:81
	ds_read2_b32 v[28:29], v6 offset0:32 offset1:97
	ds_read2_b32 v[30:31], v6 offset0:48 offset1:113
	s_waitcnt lgkmcnt(3)
	v_cvt_pk_bf16_f32 v32, v24, v25
	s_waitcnt lgkmcnt(2)
	v_cvt_pk_bf16_f32 v33, v26, v27
	s_waitcnt lgkmcnt(1)
	v_cvt_pk_bf16_f32 v34, v28, v29
	s_waitcnt lgkmcnt(0)
	v_cvt_pk_bf16_f32 v35, v30, v31
	global_store_dword v4, v32, s[8:9]
	s_add_u32 s8, s8, s17
	s_addc_u32 s9, s9, 0
	global_store_dword v4, v33, s[8:9]
	s_add_u32 s8, s8, s17
	s_addc_u32 s9, s9, 0
	global_store_dword v4, v34, s[8:9]
	s_add_u32 s8, s8, s17
	s_addc_u32 s9, s9, 0
	global_store_dword v4, v35, s[8:9]
	s_barrier
	s_cmp_eq_u32 s31, 0
	s_cbranch_scc1 .Ltc1_done
	s_mov_b32 s17, s15
	s_mov_b32 s30, s16
	s_mov_b64 s[8:9], s[12:13]
	s_add_u32 s4, s4, 84
	s_cmp_lt_u32 s4, 704
	s_cselect_b32 s31, 1, 0
	s_cbranch_scc0 .Ltc1_nonextb
	v_writelane_b32 v40, s8, 32
	v_writelane_b32 v40, s9, 33
	s_mov_b32 s7, s4
	s_mul_i32 s9, s7, 1490
	s_lshr_b32 s9, s9, 16
	s_mul_i32 s8, s9, 44
	s_sub_u32 s8, s7, s8
	s_mul_i32 s7, s8, 262144
	s_lshl_b32 s29, s9, 8
	s_add_u32 s7, s7, s29
	s_mul_i32 s29, s28, 4096
	s_add_u32 s7, s7, s29
	s_add_u32 s10, s18, s7
	s_addc_u32 s11, s19, 0
	s_lshl_b32 s7, s9, 6
	s_mul_i32 s7, s7, 5632
	s_lshl_b32 s29, s8, 7
	s_add_u32 s7, s7, s29
	s_mul_i32 s29, s28, 11264
	s_add_u32 s7, s7, s29
	s_add_u32 s12, s24, 0x1644800
	s_addc_u32 s13, s25, 0
	s_add_u32 s12, s12, s7
	s_addc_u32 s13, s13, 0
	s_mov_b32 s14, 32768
	s_mov_b32 s15, 90112
	s_movk_i32 s16, 5632

; __device__ __forceinline__ int fresh_tid(int wv) { int l; asm volatile("v_mbcnt_lo_u32_b32 %0, -1, 0\n\tv_mbcnt_hi_u32_b32 %0, -1, %0" : "=v"(l)); return wv * 64 + l; }
; #define LAS __attribute__((address_space(3)))
; __device__ __forceinline__ TDesc tconv_desc(const float* wg, const float* wu, const float* wd, const float* win, const float* wout, unsigned char* ws, int i) {
;     TDesc d; int mode = 0, tile = i;
;     if (i < 704) { d.W = wg; d.Bt = (bf16_t*)(ws + WS_WGU); d.K = 1024; d.N = DFF; mode = 1; }
;     else if (i < 1408) { d.W = wu; d.Bt = (bf16_t*)(ws + WS_WGU); d.K = 1024; d.N = DFF; mode = 2; tile = i - 704; }
;     else if (i < 2112) { d.W = wd; d.Bt = (bf16_t*)(ws + WS_WD); d.K = DFF; d.N = 1024; tile = i - 1408; }
;     else if (i < 3072) { d.W = win; d.Bt = (bf16_t*)(ws + WS_WIN); d.K = 1024; d.N = NCOLS; tile = i - 2112; }
;     else { d.W = wout; d.Bt = (bf16_t*)(ws + WS_WOUT); d.K = 1024; d.N = 1024; tile = i - 3072; }
;     const int nkt = d.K / 64; const int kt = tile % nkt, nt = tile / nkt; d.k0 = kt * 64; d.n0 = nt * 64;
;     d.brow0 = mode == 0 ? d.n0 : ((d.n0 >> 7) * 256 + (d.n0 & 127) + (mode == 2 ? 128 : 0));
;     return d;
; }
; __device__ __forceinline__ void tconv_list(const float* wg, const float* wu, const float* wd, const float* win, const float* wout, unsigned char* ws, const int ntiles, LAS float* t, const int wv) {
;     const int tid = fresh_tid(wv); const int G = gridDim.x;
;     float cur[8], nxt[8];
;     int i = blockIdx.x;
;     if (i < ntiles) { const TDesc d = tconv_desc(wg, wu, wd, win, wout, ws, i);
; #pragma unroll
;         for (int e = 0; e < 8; ++e) { const int idx = e * 512 + tid, r = idx >> 6, c = idx & 63; cur[e] = __builtin_nontemporal_load(d.W + (size_t)(d.k0 + r) * d.N + d.n0 + c); } }
;     for (; i < ntiles; i += G) {
;         const TDesc d = tconv_desc(wg, wu, wd, win, wout, ws, i);
;         { const TDesc dn = tconv_desc(wg, wu, wd, win, wout, ws, i + G < ntiles ? i + G : i);
; #pragma unroll
;             for (int e = 0; e < 8; ++e) { const int idx = e * 512 + tid, r = idx >> 6, c = idx & 63; nxt[e] = __builtin_nontemporal_load(dn.W + (size_t)(dn.k0 + r) * dn.N + dn.n0 + c); } }
.LBB0_233:
	s_cmp_lt_u32 s2, 64
	s_cbranch_scc1 .Ltc3_skip
	v_writelane_b32 v40, s4, 4
	v_writelane_b32 v40, s5, 5
	v_writelane_b32 v40, s6, 6
	v_writelane_b32 v40, s7, 7
	v_writelane_b32 v40, s8, 8
	v_writelane_b32 v40, s9, 9
	v_writelane_b32 v40, s10, 10
	v_writelane_b32 v40, s11, 11
	v_writelane_b32 v40, s12, 12
	v_writelane_b32 v40, s13, 13
	v_writelane_b32 v40, s14, 14
	v_writelane_b32 v40, s15, 15
	v_writelane_b32 v40, s16, 16
	v_writelane_b32 v40, s17, 17
	v_writelane_b32 v40, s18, 18
	v_writelane_b32 v40, s19, 19
	v_writelane_b32 v40, s20, 20
	v_writelane_b32 v40, s21, 21
	v_writelane_b32 v40, s22, 22
	v_writelane_b32 v40, s23, 23
	v_writelane_b32 v40, s24, 24
	v_writelane_b32 v40, s25, 25
	v_writelane_b32 v40, s26, 26
	v_writelane_b32 v40, s27, 27
	v_writelane_b32 v40, s28, 28
	v_writelane_b32 v40, s29, 29
	v_writelane_b32 v40, s30, 30
	v_writelane_b32 v40, s31, 31
	s_load_dwordx2 s[24:25], s[0:1], 0xd8
	s_load_dwordx2 s[26:27], s[0:1], 0xd0
	s_load_dwordx2 s[18:19], s[0:1], 0x48
	s_load_dwordx2 s[20:21], s[0:1], 0xb0
	v_mbcnt_lo_u32_b32 v0, -1, 0
	v_mbcnt_hi_u32_b32 v0, -1, v0
	s_lshr_b32 s28, s33, 6
	v_lshlrev_b32_e32 v1, 2, v0
	v_lshrrev_b32_e32 v2, 5, v0
	v_and_b32_e32 v3, 31, v0
	s_mul_i32 s7, s28, 260
	v_add_u32_e32 v5, s7, v1
	v_mul_u32_u24_e32 v6, 0x208, v3
	s_lshl_b32 s7, s28, 3
	v_lshl_add_u32 v6, v2, 2, v6
	v_add_u32_e32 v6, s7, v6
	v_lshlrev_b32_e32 v3, 2, v3
	s_sub_u32 s4, s2, 64
	s_waitcnt lgkmcnt(0)
	s_cmp_lt_u32 s4, 960
	s_cbranch_scc0 .Ltc3_seg1_0
	s_mov_b32 s7, s4
	s_and_b32 s8, s7, 15
	s_lshr_b32 s9, s7, 4
	s_mul_i32 s7, s8, 983040
	s_lshl_b32 s29, s9, 8
	s_add_u32 s7, s7, s29
	s_mul_i32 s29, s28, 15360
	s_add_u32 s7, s7, s29
	s_add_u32 s10, s18, s7
	s_addc_u32 s11, s19, 0
	s_lshl_b32 s7, s9, 6
	s_mul_i32 s7, s7, 2048
	s_lshl_b32 s29, s8, 7
	s_add_u32 s7, s7, s29
	s_mul_i32 s29, s28, 4096
	s_add_u32 s7, s7, s29
	s_add_u32 s12, s24, 0x3c4800
	s_addc_u32 s13, s25, 0
	s_add_u32 s12, s12, s7
	s_addc_u32 s13, s13, 0
	s_mov_b32 s14, 122880
	s_mov_b32 s15, 32768
	s_movk_i32 s16, 2048
	s_branch .Ltc3_segend_0

; __device__ __forceinline__ void tconv_list(const float* wg, const float* wu, const float* wd, const float* win, const float* wout, unsigned char* ws, const int ntiles, LAS float* t, const int wv) {
;     ...
;     for (; i < ntiles; i += G) {
;         const TDesc d = tconv_desc(wg, wu, wd, win, wout, ws, i);
;         { const TDesc dn = tconv_desc(wg, wu, wd, win, wout, ws, i + G < ntiles ? i + G : i);
; #pragma unroll
;             for (int e = 0; e < 8; ++e) { const int idx = e * 512 + tid, r = idx >> 6, c = idx & 63; nxt[e] = __builtin_nontemporal_load(dn.W + (size_t)(dn.k0 + r) * dn.N + dn.n0 + c); } }
.Ltc3_loop:
	s_add_u32 s4, s4, 192
	s_cmp_lt_u32 s4, 1216
	s_cselect_b32 s31, 1, 0
	s_cbranch_scc0 .Ltc3_nonexta
	v_writelane_b32 v40, s8, 32
	v_writelane_b32 v40, s9, 33
	s_cmp_lt_u32 s4, 960
	s_cbranch_scc0 .Ltc3_seg1_1
	s_mov_b32 s7, s4
	s_and_b32 s8, s7, 15
	s_lshr_b32 s9, s7, 4
	s_mul_i32 s7, s8, 983040
	s_lshl_b32 s29, s9, 8
	s_add_u32 s7, s7, s29
	s_mul_i32 s29, s28, 15360
	s_add_u32 s7, s7, s29
	s_add_u32 s10, s18, s7
	s_addc_u32 s11, s19, 0
	s_lshl_b32 s7, s9, 6
	s_mul_i32 s7, s7, 2048
	s_lshl_b32 s29, s8, 7
	s_add_u32 s7, s7, s29
	s_mul_i32 s29, s28, 4096
	s_add_u32 s7, s7, s29
	s_add_u32 s12, s24, 0x3c4800
	s_addc_u32 s13, s25, 0
	s_add_u32 s12, s12, s7
	s_addc_u32 s13, s13, 0
	s_mov_b32 s14, 122880
	s_mov_b32 s15, 32768
	s_movk_i32 s16, 2048
	s_branch .Ltc3_segend_1

; __device__ __forceinline__ unsigned cvt_pk_bf16(float lo, float hi) { const f32x2_t v = {lo, hi}; const bf16x2_t b = __builtin_convertvector(v, bf16x2_t); return __builtin_bit_cast(unsigned, b); }
; __device__ __forceinline__ void tconv_list(const float* wg, const float* wu, const float* wd, const float* win, const float* wout, unsigned char* ws, const int ntiles, LAS float* t, const int wv) {
;     ...
; #pragma unroll
;         for (int e = 0; e < 8; ++e) { const int idx = e * 512 + tid, r = idx >> 6, c = idx & 63; t[r * 65 + c] = cur[e]; }
;         __syncthreads();
; #pragma unroll
;         for (int e = 0; e < 4; ++e) { const int idx = e * 512 + tid, n = idx >> 5, kp = idx & 31;
;             const unsigned w = pg8::cvt_pk_bf16(t[(2 * kp) * 65 + n], t[(2 * kp + 1) * 65 + n]);
;             *(unsigned*)(d.Bt + (size_t)(d.brow0 + n) * d.K + d.k0 + 2 * kp) = w; }
;         __syncthreads();
; #pragma unroll
;         for (int e = 0; e < 8; ++e) cur[e] = nxt[e];
.Ltc3_havea:
	ds_write_b32 v5, v8 offset:0
	ds_write_b32 v5, v9 offset:2080
	ds_write_b32 v5, v10 offset:4160
	ds_write_b32 v5, v11 offset:6240
	ds_write_b32 v5, v12 offset:8320
	ds_write_b32 v5, v13 offset:10400
	ds_write_b32 v5, v14 offset:12480
	ds_write_b32 v5, v15 offset:14560
	v_mad_u32_u24 v4, v2, s30, v3
	s_waitcnt lgkmcnt(0)
	s_barrier
	ds_read2_b32 v[24:25], v6 offset0:0 offset1:65
	ds_read2_b32 v[26:27], v6 offset0:16 offset1:81
	ds_read2_b32 v[28:29], v6 offset0:32 offset1:97
	ds_read2_b32 v[30:31], v6 offset0:48 offset1:113
	s_waitcnt lgkmcnt(3)
	v_cvt_pk_bf16_f32 v32, v24, v25
	s_waitcnt lgkmcnt(2)
	v_cvt_pk_bf16_f32 v33, v26, v27
	s_waitcnt lgkmcnt(1)
	v_cvt_pk_bf16_f32 v34, v28, v29
	s_waitcnt lgkmcnt(0)
	v_cvt_pk_bf16_f32 v35, v30, v31
	global_store_dword v4, v32, s[8:9]
	s_add_u32 s8, s8, s17
	s_addc_u32 s9, s9, 0
	global_store_dword v4, v33, s[8:9]
	s_add_u32 s8, s8, s17
	s_addc_u32 s9, s9, 0
	global_store_dword v4, v34, s[8:9]
	s_add_u32 s8, s8, s17
	s_addc_u32 s9, s9, 0
	global_store_dword v4, v35, s[8:9]
	s_barrier
	s_cmp_eq_u32 s31, 0
	s_cbranch_scc1 .Ltc3_done
	s_mov_b32 s17, s15
	s_mov_b32 s30, s16
	s_mov_b64 s[8:9], s[12:13]
	s_add_u32 s4, s4, 192
	s_cmp_lt_u32 s4, 1216
	s_cselect_b32 s31, 1, 0
	s_cbranch_scc0 .Ltc3_nonextb
	v_writelane_b32 v40, s8, 32
	v_writelane_b32 v40, s9, 33
	s_cmp_lt_u32 s4, 960
	s_cbranch_scc0 .Ltc3_seg1_2
	s_mov_b32 s7, s4
	s_and_b32 s8, s7, 15
	s_lshr_b32 s9, s7, 4
	s_mul_i32 s7, s8, 983040
	s_lshl_b32 s29, s9, 8
	s_add_u32 s7, s7, s29
	s_mul_i32 s29, s28, 15360
	s_add_u32 s7, s7, s29
	s_add_u32 s10, s18, s7
	s_addc_u32 s11, s19, 0
	s_lshl_b32 s7, s9, 6
	s_mul_i32 s7, s7, 2048
	s_lshl_b32 s29, s8, 7
	s_add_u32 s7, s7, s29
	s_mul_i32 s29, s28, 4096
	s_add_u32 s7, s7, s29
	s_add_u32 s12, s24, 0x3c4800
	s_addc_u32 s13, s25, 0
	s_add_u32 s12, s12, s7
	s_addc_u32 s13, s13, 0
	s_mov_b32 s14, 122880
	s_mov_b32 s15, 32768
	s_movk_i32 s16, 2048
	s_branch .Ltc3_segend_2
